# y phase d-loop: per-element decay-mask direction select moved from VALU (cndmask/and/cmp chain) to SALU (s_cselect on the lane masks)
# baseline (speedup 1.0000x reference)
.LBB0_2105:
	s_lshl_b32 s16, s20, 12
	s_add_i32 s16, s16, s19
	s_or_b32 s16, s12, s16
	s_mov_b32 s17, s13
	s_lshl_b64 s[16:17], s[16:17], 2
	s_add_u32 vcc_lo, s33, s16
	s_addc_u32 vcc_hi, s18, s17
	s_lshl_b32 s100, s20, 9
	v_add_u32_e32 v212, s100, v227
	v_add_u32_e32 v213, s100, v233
	v_add_u32_e32 v214, s100, v250
	s_mulk_i32 s20, 0x4400
	v_add_u32_e32 v190, s20, v199
	ds_read_b32 v206, v212
	ds_read_b128 v[186:189], v190 offset:17408
	ds_read_b128 v[234:237], v190 offset:26112
	ds_read_b128 v[238:241], v190 offset:17440
	ds_read_b128 v[242:245], v190 offset:26144
	ds_read_b128 v[246:249], v190 offset:17472
	s_waitcnt lgkmcnt(4)
	v_mfma_f32_32x32x16_bf16 v[112:127], v[130:133], v[186:189], 0
	ds_read_b128 v[186:189], v190 offset:26176
	s_waitcnt lgkmcnt(4)
	v_mfma_f32_32x32x16_bf16 v[96:111], v[130:133], v[234:237], 0
	ds_read_b128 v[234:237], v190 offset:17504
	s_waitcnt lgkmcnt(4)
	v_mfma_f32_32x32x16_bf16 v[112:127], v[134:137], v[238:241], v[112:127]
	ds_read_b128 v[238:241], v190 offset:26208
	s_waitcnt lgkmcnt(4)
	v_mfma_f32_32x32x16_bf16 v[96:111], v[134:137], v[242:245], v[96:111]
	ds_read_b128 v[242:245], v190 offset:17536
	s_waitcnt lgkmcnt(4)
	v_mfma_f32_32x32x16_bf16 v[112:127], v[138:141], v[246:249], v[112:127]
	ds_read_b128 v[246:249], v190 offset:26240
	s_waitcnt lgkmcnt(4)
	v_mfma_f32_32x32x16_bf16 v[96:111], v[138:141], v[186:189], v[96:111]
	ds_read_b128 v[186:189], v190 offset:17568
	s_waitcnt lgkmcnt(4)
	v_mfma_f32_32x32x16_bf16 v[112:127], v[142:145], v[234:237], v[112:127]
	ds_read_b128 v[234:237], v190 offset:26272
	s_waitcnt lgkmcnt(4)
	v_mfma_f32_32x32x16_bf16 v[96:111], v[142:145], v[238:241], v[96:111]
	ds_read_b128 v[238:241], v190 offset:17600
	s_waitcnt lgkmcnt(4)
	v_mfma_f32_32x32x16_bf16 v[112:127], v[146:149], v[242:245], v[112:127]
	ds_read_b128 v[242:245], v190 offset:26304
	s_waitcnt lgkmcnt(4)
	v_mfma_f32_32x32x16_bf16 v[96:111], v[146:149], v[246:249], v[96:111]
	ds_read_b128 v[246:249], v190 offset:17632
	s_waitcnt lgkmcnt(4)
	v_mfma_f32_32x32x16_bf16 v[112:127], v[150:153], v[186:189], v[112:127]
	ds_read_b128 v[186:189], v190 offset:26336
	s_waitcnt lgkmcnt(4)
	v_mfma_f32_32x32x16_bf16 v[96:111], v[150:153], v[234:237], v[96:111]
	s_waitcnt lgkmcnt(3)
	v_mfma_f32_32x32x16_bf16 v[112:127], v[154:157], v[238:241], v[112:127]
	s_waitcnt lgkmcnt(2)
	v_mfma_f32_32x32x16_bf16 v[96:111], v[154:157], v[242:245], v[96:111]
	s_waitcnt lgkmcnt(1)
	v_mfma_f32_32x32x16_bf16 v[112:127], v[158:161], v[246:249], v[112:127]
	s_waitcnt lgkmcnt(0)
	v_mfma_f32_32x32x16_bf16 v[96:111], v[158:161], v[186:189], v[96:111]
	ds_read_b128 v[186:189], v213
	ds_read_b128 v[190:193], v213 offset:32
	ds_read_b128 v[194:197], v213 offset:64
	s_waitcnt lgkmcnt(2)
	v_mul_f32_e32 v186, 0x3fb8aa3b, v186
	ds_read_b128 v[208:211], v213 offset:96
	v_mul_f32_e32 v187, 0x3fb8aa3b, v187
	v_exp_f32_e32 v186, v186
	v_exp_f32_e32 v187, v187
	v_mul_f32_e32 v188, 0x3fb8aa3b, v188
	v_mul_f32_e32 v189, 0x3fb8aa3b, v189
	s_waitcnt lgkmcnt(2)
	v_mul_f32_e32 v190, 0x3fb8aa3b, v190
	v_mul_f32_e32 v191, 0x3fb8aa3b, v191
	v_mul_f32_e32 v192, 0x3fb8aa3b, v192
	v_mul_f32_e32 v193, 0x3fb8aa3b, v193
	s_waitcnt lgkmcnt(1)
	v_mul_f32_e32 v194, 0x3fb8aa3b, v194
	v_mul_f32_e32 v195, 0x3fb8aa3b, v195
	v_mul_f32_e32 v196, 0x3fb8aa3b, v196
	v_mul_f32_e32 v197, 0x3fb8aa3b, v197
	v_exp_f32_e32 v188, v188
	v_exp_f32_e32 v189, v189
	v_exp_f32_e32 v190, v190
	v_exp_f32_e32 v191, v191
	v_exp_f32_e32 v192, v192
	v_exp_f32_e32 v193, v193
	v_exp_f32_e32 v194, v194
	v_exp_f32_e32 v195, v195
	v_exp_f32_e32 v196, v196
	v_exp_f32_e32 v197, v197
	v_pk_fma_f32 v[64:65], v[96:97], v[186:187], v[64:65]
	v_cndmask_b32_e64 v96, 0, 1, s[4:5]
	v_cndmask_b32_e64 v97, 0, 1, s[6:7]
	v_cndmask_b32_e64 v96, v97, v96, s[14:15]
	v_and_b32_e32 v96, 1, v96
	v_pk_fma_f32 v[90:91], v[122:123], v[196:197], v[90:91]
	v_pk_fma_f32 v[88:89], v[120:121], v[194:195], v[88:89]
	v_pk_fma_f32 v[86:87], v[118:119], v[192:193], v[86:87]
	v_pk_fma_f32 v[84:85], v[116:117], v[190:191], v[84:85]
	v_pk_fma_f32 v[82:83], v[114:115], v[188:189], v[82:83]
	v_pk_fma_f32 v[80:81], v[112:113], v[186:187], v[80:81]
	v_pk_fma_f32 v[74:75], v[106:107], v[196:197], v[74:75]
	v_pk_fma_f32 v[72:73], v[104:105], v[194:195], v[72:73]
	v_pk_fma_f32 v[70:71], v[102:103], v[192:193], v[70:71]
	v_pk_fma_f32 v[68:69], v[100:101], v[190:191], v[68:69]
	v_pk_fma_f32 v[66:67], v[98:99], v[188:189], v[66:67]
	v_cmp_eq_u32_e32 vcc, 1, v96
	s_waitcnt lgkmcnt(0)
	v_mul_f32_e32 v207, 0x3fb8aa3b, v208
	v_exp_f32_e32 v208, v207
	v_mul_f32_e32 v207, 0x3fb8aa3b, v209
	v_exp_f32_e32 v209, v207
	v_mul_f32_e32 v207, 0x3fb8aa3b, v210
	v_exp_f32_e32 v210, v207
	v_mul_f32_e32 v207, 0x3fb8aa3b, v211
	v_exp_f32_e32 v211, v207
	v_pk_fma_f32 v[92:93], v[124:125], v[208:209], v[92:93]
	v_pk_fma_f32 v[76:77], v[108:109], v[208:209], v[76:77]
	v_lshl_add_u64 v[108:109], v[174:175], 0, s[16:17]
	v_pk_fma_f32 v[94:95], v[126:127], v[210:211], v[94:95]
	v_pk_fma_f32 v[78:79], v[110:111], v[210:211], v[78:79]
	v_add_u32_e32 v110, v198, v172
	s_and_saveexec_b64 s[16:17], vcc
	s_cbranch_execz .LBB0_2107
	ds_read_b128 v[100:103], v214
	ds_read_b128 v[96:99], v214 offset:32
	v_readlane_b32 s20, v252, 53
	v_readlane_b32 s21, v252, 54
	v_add_u32_e32 v111, 0x2000, v110
	s_waitcnt lgkmcnt(1)
	v_sub_f32_e32 v100, v206, v100
	s_mov_b64 s[98:99], s[20:21]
	v_readlane_b32 s20, v252, 55
	v_readlane_b32 s21, v252, 56
	v_mul_f32_e32 v100, 0x3fb8aa3b, v100
	v_sub_f32_e32 v101, v206, v101
	s_cmp_eq_u64 s[14:15], 0
	s_cselect_b64 s[98:99], s[20:21], s[98:99]
	v_readlane_b32 s20, v252, 57
	v_readlane_b32 s21, v252, 58
	v_mul_f32_e32 v101, 0x3fb8aa3b, v101
	s_mov_b64 s[100:101], s[20:21]
	v_readlane_b32 s20, v252, 59
	v_readlane_b32 s21, v252, 60
	v_cndmask_b32_e64 v100, v232, v100, s[98:99]
	v_sub_f32_e32 v102, v206, v102
	s_cmp_eq_u64 s[14:15], 0
	s_cselect_b64 s[100:101], s[20:21], s[100:101]
	v_readlane_b32 s20, v252, 61
	v_readlane_b32 s21, v252, 62
	v_mul_f32_e32 v102, 0x3fb8aa3b, v102
	s_mov_b64 s[98:99], s[20:21]
	v_readlane_b32 s20, v252, 63
	v_readlane_b32 s21, v253, 0
	v_cndmask_b32_e64 v101, v232, v101, s[100:101]
	v_sub_f32_e32 v103, v206, v103
	s_cmp_eq_u64 s[14:15], 0
	s_cselect_b64 s[98:99], s[20:21], s[98:99]
	v_readlane_b32 s20, v253, 1
	v_readlane_b32 s21, v253, 2
	v_mul_f32_e32 v103, 0x3fb8aa3b, v103
	s_mov_b64 s[100:101], s[20:21]
	v_readlane_b32 s20, v253, 3
	v_readlane_b32 s21, v253, 4
	v_cndmask_b32_e64 v102, v232, v102, s[98:99]
	s_waitcnt lgkmcnt(0)
	v_sub_f32_e32 v96, v206, v96
	s_cmp_eq_u64 s[14:15], 0
	s_cselect_b64 s[100:101], s[20:21], s[100:101]
	v_readlane_b32 s20, v253, 5
	v_readlane_b32 s21, v253, 6
	v_mul_f32_e32 v96, 0x3fb8aa3b, v96
	s_mov_b64 s[98:99], s[20:21]
	v_readlane_b32 s20, v253, 7
	v_readlane_b32 s21, v253, 8
	v_cndmask_b32_e64 v103, v232, v103, s[100:101]
	v_sub_f32_e32 v97, v206, v97
	s_cmp_eq_u64 s[14:15], 0
	s_cselect_b64 s[98:99], s[20:21], s[98:99]
	v_readlane_b32 s20, v253, 9
	v_readlane_b32 s21, v253, 10
	v_mul_f32_e32 v97, 0x3fb8aa3b, v97
	s_mov_b64 s[100:101], s[20:21]
	v_readlane_b32 s20, v253, 11
	v_readlane_b32 s21, v253, 12
	v_cndmask_b32_e64 v96, v232, v96, s[98:99]
	v_sub_f32_e32 v98, v206, v98
	s_cmp_eq_u64 s[14:15], 0
	s_cselect_b64 s[100:101], s[20:21], s[100:101]
	v_readlane_b32 s20, v253, 13
	v_readlane_b32 s21, v253, 14
	v_mul_f32_e32 v98, 0x3fb8aa3b, v98
	s_mov_b64 s[98:99], s[20:21]
	v_readlane_b32 s20, v253, 15
	v_readlane_b32 s21, v253, 16
	v_cndmask_b32_e64 v97, v232, v97, s[100:101]
	v_sub_f32_e32 v99, v206, v99
	s_cmp_eq_u64 s[14:15], 0
	s_cselect_b64 s[98:99], s[20:21], s[98:99]
	v_readlane_b32 s20, v253, 17
	v_readlane_b32 s21, v253, 18
	v_mul_f32_e32 v99, 0x3fb8aa3b, v99
	s_mov_b64 s[100:101], s[20:21]
	v_readlane_b32 s20, v253, 19
	v_readlane_b32 s21, v253, 20
	v_cndmask_b32_e64 v98, v232, v98, s[98:99]
	v_exp_f32_e32 v100, v100
	s_cmp_eq_u64 s[14:15], 0
	s_cselect_b64 s[100:101], s[20:21], s[100:101]
	v_exp_f32_e32 v101, v101
	v_exp_f32_e32 v102, v102
	v_cndmask_b32_e64 v99, v232, v99, s[100:101]
	v_exp_f32_e32 v103, v103
	v_exp_f32_e32 v96, v96
	v_exp_f32_e32 v97, v97
	v_exp_f32_e32 v98, v98
	v_exp_f32_e32 v99, v99
	v_pk_mul_f32 v[100:101], v[0:1], v[100:101]
	v_pk_mul_f32 v[102:103], v[2:3], v[102:103]
	v_pk_mul_f32 v[96:97], v[4:5], v[96:97]
	v_pk_mul_f32 v[98:99], v[6:7], v[98:99]
	v_cvt_pk_bf16_f32 v100, v100, v101
	v_cvt_pk_bf16_f32 v101, v102, v103
	v_cvt_pk_bf16_f32 v102, v96, v97
	v_cvt_pk_bf16_f32 v103, v98, v99
	ds_read2_b64 v[104:107], v110 offset1:2
	ds_read2_b64 v[96:99], v110 offset0:4 offset1:6
	s_waitcnt lgkmcnt(1)
	v_mfma_f32_32x32x16_bf16 v[80:95], v[100:103], v[104:107], v[80:95]
	ds_read2_b64 v[104:107], v111 offset0:64 offset1:66
	v_readlane_b32 s20, v253, 21
	v_readlane_b32 s21, v253, 22
	s_nop 1
	s_mov_b64 s[98:99], s[20:21]
	v_readlane_b32 s20, v253, 23
	s_waitcnt lgkmcnt(0)
	v_mfma_f32_32x32x16_bf16 v[64:79], v[100:103], v[104:107], v[64:79]
	ds_read_b128 v[104:107], v214 offset:64
	ds_read_b128 v[100:103], v214 offset:96
	v_readlane_b32 s21, v253, 24
	s_waitcnt lgkmcnt(1)
	v_sub_f32_e32 v104, v206, v104
	s_cmp_eq_u64 s[14:15], 0
	s_cselect_b64 s[98:99], s[20:21], s[98:99]
	v_readlane_b32 s20, v253, 25
	v_readlane_b32 s21, v253, 26
	v_mul_f32_e32 v104, 0x3fb8aa3b, v104
	s_mov_b64 s[100:101], s[20:21]
	v_readlane_b32 s20, v253, 27
	v_readlane_b32 s21, v253, 28
	v_cndmask_b32_e64 v104, v232, v104, s[98:99]
	v_sub_f32_e32 v105, v206, v105
	s_cmp_eq_u64 s[14:15], 0
	s_cselect_b64 s[100:101], s[20:21], s[100:101]
	v_readlane_b32 s20, v253, 29
	v_readlane_b32 s21, v253, 30
	v_mul_f32_e32 v105, 0x3fb8aa3b, v105
	s_mov_b64 s[98:99], s[20:21]
	v_readlane_b32 s20, v253, 31
	v_readlane_b32 s21, v253, 32
	v_cndmask_b32_e64 v105, v232, v105, s[100:101]
	v_sub_f32_e32 v106, v206, v106
	s_cmp_eq_u64 s[14:15], 0
	s_cselect_b64 s[98:99], s[20:21], s[98:99]
	v_readlane_b32 s20, v253, 33
	v_readlane_b32 s21, v253, 34
	v_mul_f32_e32 v106, 0x3fb8aa3b, v106
	s_mov_b64 s[100:101], s[20:21]
	v_readlane_b32 s20, v253, 35
	v_readlane_b32 s21, v253, 36
	v_cndmask_b32_e64 v106, v232, v106, s[98:99]
	v_sub_f32_e32 v107, v206, v107
	s_cmp_eq_u64 s[14:15], 0
	s_cselect_b64 s[100:101], s[20:21], s[100:101]
	v_readlane_b32 s20, v253, 37
	v_readlane_b32 s21, v253, 38
	v_mul_f32_e32 v107, 0x3fb8aa3b, v107
	s_mov_b64 s[98:99], s[20:21]
	v_readlane_b32 s20, v253, 39
	v_readlane_b32 s21, v253, 40
	v_cndmask_b32_e64 v107, v232, v107, s[100:101]
	s_waitcnt lgkmcnt(0)
	v_sub_f32_e32 v100, v206, v100
	s_cmp_eq_u64 s[14:15], 0
	s_cselect_b64 s[98:99], s[20:21], s[98:99]
	v_readlane_b32 s20, v253, 41
	v_readlane_b32 s21, v253, 42
	v_mul_f32_e32 v100, 0x3fb8aa3b, v100
	s_mov_b64 s[100:101], s[20:21]
	v_readlane_b32 s20, v253, 43
	v_readlane_b32 s21, v253, 44
	v_sub_f32_e32 v101, v206, v101
	v_cndmask_b32_e64 v100, v232, v100, s[98:99]
	s_cmp_eq_u64 s[14:15], 0
	s_cselect_b64 s[100:101], s[20:21], s[100:101]
	v_mul_f32_e32 v101, 0x3fb8aa3b, v101
	v_exp_f32_e32 v100, v100
	v_cndmask_b32_e64 v101, v232, v101, s[100:101]
	v_exp_f32_e32 v101, v101
	v_readlane_b32 s20, v253, 45
	v_readlane_b32 s21, v253, 46
	v_exp_f32_e32 v104, v104
	v_pk_mul_f32 v[112:113], v[12:13], v[100:101]
	s_mov_b64 s[98:99], s[20:21]
	v_readlane_b32 s20, v253, 47
	v_readlane_b32 s21, v253, 48
	v_exp_f32_e32 v105, v105
	v_exp_f32_e32 v106, v106
	s_cmp_eq_u64 s[14:15], 0
	s_cselect_b64 s[98:99], s[20:21], s[98:99]
	v_readlane_b32 s20, v253, 49
	v_readlane_b32 s21, v253, 50
	s_mov_b64 s[100:101], s[20:21]
	v_readlane_b32 s20, v253, 51
	v_readlane_b32 s21, v253, 52
	v_sub_f32_e32 v100, v206, v102
	v_mul_f32_e32 v100, 0x3fb8aa3b, v100
	v_cndmask_b32_e64 v100, v232, v100, s[98:99]
	s_cmp_eq_u64 s[14:15], 0
	s_cselect_b64 s[100:101], s[20:21], s[100:101]
	v_sub_f32_e32 v101, v206, v103
	v_mul_f32_e32 v101, 0x3fb8aa3b, v101
	v_cndmask_b32_e64 v101, v232, v101, s[100:101]
	v_exp_f32_e32 v107, v107
	v_exp_f32_e32 v100, v100
	v_exp_f32_e32 v101, v101
	v_pk_mul_f32 v[104:105], v[8:9], v[104:105]
	v_pk_mul_f32 v[106:107], v[10:11], v[106:107]
	v_cvt_pk_bf16_f32 v102, v112, v113
	v_pk_mul_f32 v[114:115], v[14:15], v[100:101]
	v_cvt_pk_bf16_f32 v100, v104, v105
	v_cvt_pk_bf16_f32 v101, v106, v107
	v_cvt_pk_bf16_f32 v103, v114, v115
	s_nop 1
	v_mfma_f32_32x32x16_bf16 v[80:95], v[100:103], v[96:99], v[80:95]
	ds_read2_b64 v[96:99], v111 offset0:68 offset1:70
	s_waitcnt lgkmcnt(0)
	v_mfma_f32_32x32x16_bf16 v[64:79], v[100:103], v[96:99], v[64:79]
.LBB0_2107:
	s_or_b64 exec, exec, s[16:17]
	v_cndmask_b32_e64 v96, 0, 1, s[74:75]
	v_cndmask_b32_e64 v97, 0, 1, s[76:77]
	v_cndmask_b32_e64 v96, v97, v96, s[14:15]
	v_and_b32_e32 v96, 1, v96
	v_cmp_eq_u32_e32 vcc, 1, v96
	s_and_saveexec_b64 s[16:17], vcc
	s_cbranch_execz .LBB0_2109
	ds_read_b128 v[100:103], v214 offset:128
	ds_read_b128 v[96:99], v214 offset:160
	v_readlane_b32 s20, v253, 53
	v_readlane_b32 s21, v253, 54
	v_add_u32_e32 v111, 0x2000, v110
	s_waitcnt lgkmcnt(1)
	v_sub_f32_e32 v100, v206, v100
	s_mov_b64 s[98:99], s[20:21]
	v_readlane_b32 s20, v253, 55
	v_readlane_b32 s21, v253, 56
	v_mul_f32_e32 v100, 0x3fb8aa3b, v100
	v_sub_f32_e32 v101, v206, v101
	s_cmp_eq_u64 s[14:15], 0
	s_cselect_b64 s[98:99], s[20:21], s[98:99]
	v_readlane_b32 s20, v253, 57
	v_readlane_b32 s21, v253, 58
	v_mul_f32_e32 v101, 0x3fb8aa3b, v101
	s_mov_b64 s[100:101], s[20:21]
	v_readlane_b32 s20, v253, 59
	v_readlane_b32 s21, v253, 60
	v_cndmask_b32_e64 v100, v232, v100, s[98:99]
	v_sub_f32_e32 v102, v206, v102
	s_cmp_eq_u64 s[14:15], 0
	s_cselect_b64 s[100:101], s[20:21], s[100:101]
	v_readlane_b32 s20, v253, 61
	v_readlane_b32 s21, v253, 62
	v_mul_f32_e32 v102, 0x3fb8aa3b, v102
	s_mov_b64 s[98:99], s[20:21]
	v_readlane_b32 s20, v253, 63
	v_readlane_b32 s21, v254, 0
	v_cndmask_b32_e64 v101, v232, v101, s[100:101]
	v_sub_f32_e32 v103, v206, v103
	s_cmp_eq_u64 s[14:15], 0
	s_cselect_b64 s[98:99], s[20:21], s[98:99]
	v_readlane_b32 s20, v254, 1
	v_readlane_b32 s21, v254, 2
	v_mul_f32_e32 v103, 0x3fb8aa3b, v103
	s_mov_b64 s[100:101], s[20:21]
	v_readlane_b32 s20, v254, 3
	v_readlane_b32 s21, v254, 4
	v_cndmask_b32_e64 v102, v232, v102, s[98:99]
	s_waitcnt lgkmcnt(0)
	v_sub_f32_e32 v96, v206, v96
	s_cmp_eq_u64 s[14:15], 0
	s_cselect_b64 s[100:101], s[20:21], s[100:101]
	v_readlane_b32 s20, v254, 5
	v_readlane_b32 s21, v254, 6
	v_mul_f32_e32 v96, 0x3fb8aa3b, v96
	s_mov_b64 s[98:99], s[20:21]
	v_readlane_b32 s20, v254, 7
	v_readlane_b32 s21, v254, 8
	v_cndmask_b32_e64 v103, v232, v103, s[100:101]
	v_sub_f32_e32 v97, v206, v97
	s_cmp_eq_u64 s[14:15], 0
	s_cselect_b64 s[98:99], s[20:21], s[98:99]
	v_readlane_b32 s20, v254, 9
	v_readlane_b32 s21, v254, 10
	v_mul_f32_e32 v97, 0x3fb8aa3b, v97
	s_mov_b64 s[100:101], s[20:21]
	v_readlane_b32 s20, v254, 11
	v_readlane_b32 s21, v254, 12
	v_cndmask_b32_e64 v96, v232, v96, s[98:99]
	v_sub_f32_e32 v98, v206, v98
	s_cmp_eq_u64 s[14:15], 0
	s_cselect_b64 s[100:101], s[20:21], s[100:101]
	v_readlane_b32 s20, v254, 13
	v_readlane_b32 s21, v254, 14
	v_mul_f32_e32 v98, 0x3fb8aa3b, v98
	s_mov_b64 s[98:99], s[20:21]
	v_readlane_b32 s20, v254, 15
	v_readlane_b32 s21, v254, 16
	v_cndmask_b32_e64 v97, v232, v97, s[100:101]
	v_sub_f32_e32 v99, v206, v99
	s_cmp_eq_u64 s[14:15], 0
	s_cselect_b64 s[98:99], s[20:21], s[98:99]
	v_readlane_b32 s20, v254, 17
	v_readlane_b32 s21, v254, 18
	v_mul_f32_e32 v99, 0x3fb8aa3b, v99
	s_mov_b64 s[100:101], s[20:21]
	v_readlane_b32 s20, v254, 19
	v_readlane_b32 s21, v254, 20
	v_cndmask_b32_e64 v98, v232, v98, s[98:99]
	v_exp_f32_e32 v100, v100
	s_cmp_eq_u64 s[14:15], 0
	s_cselect_b64 s[100:101], s[20:21], s[100:101]
	v_exp_f32_e32 v101, v101
	v_exp_f32_e32 v102, v102
	v_cndmask_b32_e64 v99, v232, v99, s[100:101]
	v_exp_f32_e32 v103, v103
	v_exp_f32_e32 v96, v96
	v_exp_f32_e32 v97, v97
	v_exp_f32_e32 v98, v98
	v_exp_f32_e32 v99, v99
	v_pk_mul_f32 v[100:101], v[16:17], v[100:101]
	v_pk_mul_f32 v[102:103], v[18:19], v[102:103]
	v_pk_mul_f32 v[96:97], v[20:21], v[96:97]
	v_pk_mul_f32 v[98:99], v[22:23], v[98:99]
	v_cvt_pk_bf16_f32 v100, v100, v101
	v_cvt_pk_bf16_f32 v101, v102, v103
	v_cvt_pk_bf16_f32 v102, v96, v97
	v_cvt_pk_bf16_f32 v103, v98, v99
	ds_read2_b64 v[104:107], v110 offset0:8 offset1:10
	ds_read2_b64 v[96:99], v110 offset0:12 offset1:14
	s_waitcnt lgkmcnt(1)
	v_mfma_f32_32x32x16_bf16 v[80:95], v[100:103], v[104:107], v[80:95]
	ds_read2_b64 v[104:107], v111 offset0:72 offset1:74
	v_readlane_b32 s20, v254, 21
	v_readlane_b32 s21, v254, 22
	s_nop 1
	s_mov_b64 s[98:99], s[20:21]
	v_readlane_b32 s20, v254, 23
	s_waitcnt lgkmcnt(0)
	v_mfma_f32_32x32x16_bf16 v[64:79], v[100:103], v[104:107], v[64:79]
	ds_read_b128 v[104:107], v214 offset:192
	ds_read_b128 v[100:103], v214 offset:224
	v_readlane_b32 s21, v254, 24
	s_waitcnt lgkmcnt(1)
	v_sub_f32_e32 v104, v206, v104
	s_cmp_eq_u64 s[14:15], 0
	s_cselect_b64 s[98:99], s[20:21], s[98:99]
	v_readlane_b32 s20, v254, 25
	v_readlane_b32 s21, v254, 26
	v_mul_f32_e32 v104, 0x3fb8aa3b, v104
	s_mov_b64 s[100:101], s[20:21]
	v_readlane_b32 s20, v254, 27
	v_readlane_b32 s21, v254, 28
	v_cndmask_b32_e64 v104, v232, v104, s[98:99]
	v_sub_f32_e32 v105, v206, v105
	s_cmp_eq_u64 s[14:15], 0
	s_cselect_b64 s[100:101], s[20:21], s[100:101]
	v_readlane_b32 s20, v254, 29
	v_readlane_b32 s21, v254, 30
	v_mul_f32_e32 v105, 0x3fb8aa3b, v105
	s_mov_b64 s[98:99], s[20:21]
	v_readlane_b32 s20, v254, 31
	v_readlane_b32 s21, v254, 32
	v_cndmask_b32_e64 v105, v232, v105, s[100:101]
	v_sub_f32_e32 v106, v206, v106
	s_cmp_eq_u64 s[14:15], 0
	s_cselect_b64 s[98:99], s[20:21], s[98:99]
	v_readlane_b32 s20, v254, 33
	v_readlane_b32 s21, v254, 34
	v_mul_f32_e32 v106, 0x3fb8aa3b, v106
	s_mov_b64 s[100:101], s[20:21]
	v_readlane_b32 s20, v254, 35
	v_readlane_b32 s21, v254, 36
	v_cndmask_b32_e64 v106, v232, v106, s[98:99]
	v_sub_f32_e32 v107, v206, v107
	s_cmp_eq_u64 s[14:15], 0
	s_cselect_b64 s[100:101], s[20:21], s[100:101]
	v_readlane_b32 s20, v254, 37
	v_readlane_b32 s21, v254, 38
	v_mul_f32_e32 v107, 0x3fb8aa3b, v107
	s_mov_b64 s[98:99], s[20:21]
	v_readlane_b32 s20, v254, 39
	v_readlane_b32 s21, v254, 40
	v_cndmask_b32_e64 v107, v232, v107, s[100:101]
	s_waitcnt lgkmcnt(0)
	v_sub_f32_e32 v100, v206, v100
	s_cmp_eq_u64 s[14:15], 0
	s_cselect_b64 s[98:99], s[20:21], s[98:99]
	v_readlane_b32 s20, v254, 41
	v_readlane_b32 s21, v254, 42
	v_mul_f32_e32 v100, 0x3fb8aa3b, v100
	s_mov_b64 s[100:101], s[20:21]
	v_readlane_b32 s20, v254, 43
	v_readlane_b32 s21, v254, 44
	v_sub_f32_e32 v101, v206, v101
	v_cndmask_b32_e64 v100, v232, v100, s[98:99]
	s_cmp_eq_u64 s[14:15], 0
	s_cselect_b64 s[100:101], s[20:21], s[100:101]
	v_mul_f32_e32 v101, 0x3fb8aa3b, v101
	v_exp_f32_e32 v100, v100
	v_cndmask_b32_e64 v101, v232, v101, s[100:101]
	v_exp_f32_e32 v101, v101
	v_readlane_b32 s20, v254, 45
	v_readlane_b32 s21, v254, 46
	v_exp_f32_e32 v104, v104
	v_pk_mul_f32 v[112:113], v[28:29], v[100:101]
	s_mov_b64 s[98:99], s[20:21]
	v_readlane_b32 s20, v254, 47
	v_readlane_b32 s21, v254, 48
	v_exp_f32_e32 v105, v105
	v_exp_f32_e32 v106, v106
	s_cmp_eq_u64 s[14:15], 0
	s_cselect_b64 s[98:99], s[20:21], s[98:99]
	v_readlane_b32 s20, v254, 49
	v_readlane_b32 s21, v254, 50
	s_mov_b64 s[100:101], s[20:21]
	v_readlane_b32 s20, v254, 51
	v_readlane_b32 s21, v254, 52
	v_sub_f32_e32 v100, v206, v102
	v_mul_f32_e32 v100, 0x3fb8aa3b, v100
	v_cndmask_b32_e64 v100, v232, v100, s[98:99]
	s_cmp_eq_u64 s[14:15], 0
	s_cselect_b64 s[100:101], s[20:21], s[100:101]
	v_sub_f32_e32 v101, v206, v103
	v_mul_f32_e32 v101, 0x3fb8aa3b, v101
	v_cndmask_b32_e64 v101, v232, v101, s[100:101]
	v_exp_f32_e32 v107, v107
	v_exp_f32_e32 v100, v100
	v_exp_f32_e32 v101, v101
	v_pk_mul_f32 v[104:105], v[24:25], v[104:105]
	v_pk_mul_f32 v[106:107], v[26:27], v[106:107]
	v_cvt_pk_bf16_f32 v102, v112, v113
	v_pk_mul_f32 v[114:115], v[30:31], v[100:101]
	v_cvt_pk_bf16_f32 v100, v104, v105
	v_cvt_pk_bf16_f32 v101, v106, v107
	v_cvt_pk_bf16_f32 v103, v114, v115
	s_nop 1
	v_mfma_f32_32x32x16_bf16 v[80:95], v[100:103], v[96:99], v[80:95]
	ds_read2_b64 v[96:99], v111 offset0:76 offset1:78
	s_waitcnt lgkmcnt(0)
	v_mfma_f32_32x32x16_bf16 v[64:79], v[100:103], v[96:99], v[64:79]
.LBB0_2109:
	s_or_b64 exec, exec, s[16:17]
	v_cndmask_b32_e64 v96, 0, 1, s[50:51]
	v_cndmask_b32_e64 v97, 0, 1, s[52:53]
	v_cndmask_b32_e64 v96, v97, v96, s[14:15]
	v_and_b32_e32 v96, 1, v96
	v_cmp_eq_u32_e32 vcc, 1, v96
	s_and_saveexec_b64 s[16:17], vcc
	s_cbranch_execz .LBB0_2111
	ds_read_b128 v[100:103], v214 offset:256
	ds_read_b128 v[96:99], v214 offset:288
	v_readlane_b32 s20, v254, 53
	v_readlane_b32 s21, v254, 54
	v_add_u32_e32 v111, 0x2000, v110
	s_waitcnt lgkmcnt(1)
	v_sub_f32_e32 v100, v206, v100
	s_mov_b64 s[98:99], s[20:21]
	v_readlane_b32 s20, v254, 55
	v_readlane_b32 s21, v254, 56
	v_mul_f32_e32 v100, 0x3fb8aa3b, v100
	v_sub_f32_e32 v101, v206, v101
	s_cmp_eq_u64 s[14:15], 0
	s_cselect_b64 s[98:99], s[20:21], s[98:99]
	v_readlane_b32 s20, v254, 57
	v_readlane_b32 s21, v254, 58
	v_mul_f32_e32 v101, 0x3fb8aa3b, v101
	s_mov_b64 s[100:101], s[20:21]
	v_readlane_b32 s20, v254, 59
	v_readlane_b32 s21, v254, 60
	v_cndmask_b32_e64 v100, v232, v100, s[98:99]
	v_sub_f32_e32 v102, v206, v102
	s_cmp_eq_u64 s[14:15], 0
	s_cselect_b64 s[100:101], s[20:21], s[100:101]
	v_readlane_b32 s20, v254, 61
	v_readlane_b32 s21, v254, 62
	v_mul_f32_e32 v102, 0x3fb8aa3b, v102
	s_mov_b64 s[98:99], s[20:21]
	v_readlane_b32 s20, v254, 63
	v_readlane_b32 s21, v255, 0
	v_cndmask_b32_e64 v101, v232, v101, s[100:101]
	v_sub_f32_e32 v103, v206, v103
	s_cmp_eq_u64 s[14:15], 0
	s_cselect_b64 s[98:99], s[20:21], s[98:99]
	v_readlane_b32 s20, v255, 1
	v_readlane_b32 s21, v255, 2
	v_mul_f32_e32 v103, 0x3fb8aa3b, v103
	s_mov_b64 s[100:101], s[20:21]
	v_readlane_b32 s20, v255, 3
	v_readlane_b32 s21, v255, 4
	v_cndmask_b32_e64 v102, v232, v102, s[98:99]
	s_waitcnt lgkmcnt(0)
	v_sub_f32_e32 v96, v206, v96
	s_cmp_eq_u64 s[14:15], 0
	s_cselect_b64 s[100:101], s[20:21], s[100:101]
	v_readlane_b32 s20, v255, 5
	v_readlane_b32 s21, v255, 6
	v_mul_f32_e32 v96, 0x3fb8aa3b, v96
	s_mov_b64 s[98:99], s[20:21]
	v_readlane_b32 s20, v255, 7
	v_readlane_b32 s21, v255, 8
	v_cndmask_b32_e64 v103, v232, v103, s[100:101]
	v_sub_f32_e32 v97, v206, v97
	s_cmp_eq_u64 s[14:15], 0
	s_cselect_b64 s[98:99], s[20:21], s[98:99]
	v_readlane_b32 s20, v255, 9
	v_readlane_b32 s21, v255, 10
	v_mul_f32_e32 v97, 0x3fb8aa3b, v97
	s_mov_b64 s[100:101], s[20:21]
	v_readlane_b32 s20, v255, 11
	v_readlane_b32 s21, v255, 12
	v_cndmask_b32_e64 v96, v232, v96, s[98:99]
	v_sub_f32_e32 v98, v206, v98
	s_cmp_eq_u64 s[14:15], 0
	s_cselect_b64 s[100:101], s[20:21], s[100:101]
	v_readlane_b32 s20, v255, 13
	v_readlane_b32 s21, v255, 14
	v_mul_f32_e32 v98, 0x3fb8aa3b, v98
	s_mov_b64 s[98:99], s[20:21]
	v_readlane_b32 s20, v255, 15
	v_readlane_b32 s21, v255, 16
	v_cndmask_b32_e64 v97, v232, v97, s[100:101]
	v_sub_f32_e32 v99, v206, v99
	s_cmp_eq_u64 s[14:15], 0
	s_cselect_b64 s[98:99], s[20:21], s[98:99]
	v_readlane_b32 s20, v255, 17
	v_readlane_b32 s21, v255, 18
	v_mul_f32_e32 v99, 0x3fb8aa3b, v99
	s_mov_b64 s[100:101], s[20:21]
	v_readlane_b32 s20, v255, 19
	v_readlane_b32 s21, v255, 20
	v_cndmask_b32_e64 v98, v232, v98, s[98:99]
	v_exp_f32_e32 v100, v100
	s_cmp_eq_u64 s[14:15], 0
	s_cselect_b64 s[100:101], s[20:21], s[100:101]
	v_exp_f32_e32 v101, v101
	v_exp_f32_e32 v102, v102
	v_cndmask_b32_e64 v99, v232, v99, s[100:101]
	v_exp_f32_e32 v103, v103
	v_exp_f32_e32 v96, v96
	v_exp_f32_e32 v97, v97
	v_exp_f32_e32 v98, v98
	v_exp_f32_e32 v99, v99
	v_pk_mul_f32 v[100:101], v[32:33], v[100:101]
	v_pk_mul_f32 v[102:103], v[34:35], v[102:103]
	v_pk_mul_f32 v[96:97], v[36:37], v[96:97]
	v_pk_mul_f32 v[98:99], v[38:39], v[98:99]
	v_cvt_pk_bf16_f32 v100, v100, v101
	v_cvt_pk_bf16_f32 v101, v102, v103
	v_cvt_pk_bf16_f32 v102, v96, v97
	v_cvt_pk_bf16_f32 v103, v98, v99
	ds_read2_b64 v[104:107], v110 offset0:16 offset1:18
	ds_read2_b64 v[96:99], v110 offset0:20 offset1:22
	s_waitcnt lgkmcnt(1)
	v_mfma_f32_32x32x16_bf16 v[80:95], v[100:103], v[104:107], v[80:95]
	ds_read2_b64 v[104:107], v111 offset0:80 offset1:82
	v_readlane_b32 s20, v255, 21
	v_readlane_b32 s21, v255, 22
	s_nop 1
	s_mov_b64 s[98:99], s[20:21]
	v_readlane_b32 s20, v255, 23
	s_waitcnt lgkmcnt(0)
	v_mfma_f32_32x32x16_bf16 v[64:79], v[100:103], v[104:107], v[64:79]
	ds_read_b128 v[104:107], v214 offset:320
	ds_read_b128 v[100:103], v214 offset:352
	v_readlane_b32 s21, v255, 24
	s_waitcnt lgkmcnt(1)
	v_sub_f32_e32 v104, v206, v104
	s_cmp_eq_u64 s[14:15], 0
	s_cselect_b64 s[98:99], s[20:21], s[98:99]
	v_readlane_b32 s20, v255, 25
	v_readlane_b32 s21, v255, 26
	v_mul_f32_e32 v104, 0x3fb8aa3b, v104
	s_mov_b64 s[100:101], s[20:21]
	v_readlane_b32 s20, v255, 27
	v_readlane_b32 s21, v255, 28
	v_cndmask_b32_e64 v104, v232, v104, s[98:99]
	v_sub_f32_e32 v105, v206, v105
	s_cmp_eq_u64 s[14:15], 0
	s_cselect_b64 s[100:101], s[20:21], s[100:101]
	v_readlane_b32 s20, v255, 29
	v_readlane_b32 s21, v255, 30
	v_mul_f32_e32 v105, 0x3fb8aa3b, v105
	s_mov_b64 s[98:99], s[20:21]
	v_readlane_b32 s20, v255, 31
	v_readlane_b32 s21, v255, 32
	v_cndmask_b32_e64 v105, v232, v105, s[100:101]
	v_sub_f32_e32 v106, v206, v106
	s_cmp_eq_u64 s[14:15], 0
	s_cselect_b64 s[98:99], s[20:21], s[98:99]
	v_readlane_b32 s20, v255, 33
	v_readlane_b32 s21, v255, 34
	v_mul_f32_e32 v106, 0x3fb8aa3b, v106
	s_mov_b64 s[100:101], s[20:21]
	v_readlane_b32 s20, v255, 35
	v_readlane_b32 s21, v255, 36
	v_cndmask_b32_e64 v106, v232, v106, s[98:99]
	v_sub_f32_e32 v107, v206, v107
	s_cmp_eq_u64 s[14:15], 0
	s_cselect_b64 s[100:101], s[20:21], s[100:101]
	v_readlane_b32 s20, v255, 37
	v_readlane_b32 s21, v255, 38
	v_mul_f32_e32 v107, 0x3fb8aa3b, v107
	s_mov_b64 s[98:99], s[20:21]
	v_readlane_b32 s20, v255, 39
	v_readlane_b32 s21, v255, 40
	v_cndmask_b32_e64 v107, v232, v107, s[100:101]
	s_waitcnt lgkmcnt(0)
	v_sub_f32_e32 v100, v206, v100
	s_cmp_eq_u64 s[14:15], 0
	s_cselect_b64 s[98:99], s[20:21], s[98:99]
	v_readlane_b32 s20, v255, 41
	v_readlane_b32 s21, v255, 42
	v_mul_f32_e32 v100, 0x3fb8aa3b, v100
	s_mov_b64 s[100:101], s[20:21]
	v_readlane_b32 s20, v255, 43
	v_readlane_b32 s21, v255, 44
	v_sub_f32_e32 v101, v206, v101
	v_cndmask_b32_e64 v100, v232, v100, s[98:99]
	s_cmp_eq_u64 s[14:15], 0
	s_cselect_b64 s[100:101], s[20:21], s[100:101]
	v_mul_f32_e32 v101, 0x3fb8aa3b, v101
	v_exp_f32_e32 v100, v100
	v_cndmask_b32_e64 v101, v232, v101, s[100:101]
	v_exp_f32_e32 v101, v101
	v_readlane_b32 s20, v255, 45
	v_readlane_b32 s21, v255, 46
	v_exp_f32_e32 v104, v104
	v_pk_mul_f32 v[112:113], v[44:45], v[100:101]
	s_mov_b64 s[98:99], s[20:21]
	v_readlane_b32 s20, v255, 47
	v_readlane_b32 s21, v255, 48
	v_exp_f32_e32 v105, v105
	v_exp_f32_e32 v106, v106
	s_cmp_eq_u64 s[14:15], 0
	s_cselect_b64 s[98:99], s[20:21], s[98:99]
	v_sub_f32_e32 v100, v206, v102
	v_mul_f32_e32 v100, 0x3fb8aa3b, v100
	v_cndmask_b32_e64 v100, v232, v100, s[98:99]
	s_cmp_lg_u64 s[14:15], 0
	s_cselect_b64 s[98:99], s[24:25], s[26:27]
	v_sub_f32_e32 v101, v206, v103
	v_mul_f32_e32 v101, 0x3fb8aa3b, v101
	v_cndmask_b32_e64 v101, v232, v101, s[98:99]
	v_exp_f32_e32 v107, v107
	v_exp_f32_e32 v100, v100
	v_exp_f32_e32 v101, v101
	v_pk_mul_f32 v[104:105], v[40:41], v[104:105]
	v_pk_mul_f32 v[106:107], v[42:43], v[106:107]
	v_cvt_pk_bf16_f32 v102, v112, v113
	v_pk_mul_f32 v[114:115], v[46:47], v[100:101]
	v_cvt_pk_bf16_f32 v100, v104, v105
	v_cvt_pk_bf16_f32 v101, v106, v107
	v_cvt_pk_bf16_f32 v103, v114, v115
	s_nop 1
	v_mfma_f32_32x32x16_bf16 v[80:95], v[100:103], v[96:99], v[80:95]
	ds_read2_b64 v[96:99], v111 offset0:84 offset1:86
	s_waitcnt lgkmcnt(0)
	v_mfma_f32_32x32x16_bf16 v[64:79], v[100:103], v[96:99], v[64:79]
.LBB0_2111:
	s_or_b64 exec, exec, s[16:17]
	v_cndmask_b32_e64 v96, 0, 1, s[28:29]
	v_cndmask_b32_e64 v97, 0, 1, s[30:31]
	v_cndmask_b32_e64 v96, v97, v96, s[14:15]
	v_and_b32_e32 v96, 1, v96
	v_cmp_eq_u32_e32 vcc, 1, v96
	s_and_saveexec_b64 s[16:17], vcc
	s_cbranch_execz .LBB0_2104
	ds_read_b128 v[100:103], v214 offset:384
	ds_read_b128 v[96:99], v214 offset:416
	s_cmp_lg_u64 s[14:15], 0
	s_cselect_b64 s[98:99], s[34:35], s[36:37]
	s_waitcnt lgkmcnt(1)
	v_sub_f32_e32 v100, v206, v100
	v_mul_f32_e32 v100, 0x3fb8aa3b, v100
	v_cndmask_b32_e64 v100, v232, v100, s[98:99]
	s_cmp_lg_u64 s[14:15], 0
	s_cselect_b64 s[98:99], s[38:39], s[40:41]
	v_sub_f32_e32 v101, v206, v101
	v_mul_f32_e32 v101, 0x3fb8aa3b, v101
	v_cndmask_b32_e64 v101, v232, v101, s[98:99]
	s_cmp_lg_u64 s[14:15], 0
	s_cselect_b64 s[98:99], s[42:43], s[44:45]
	v_sub_f32_e32 v102, v206, v102
	v_mul_f32_e32 v102, 0x3fb8aa3b, v102
	v_cndmask_b32_e64 v102, v232, v102, s[98:99]
	s_cmp_lg_u64 s[14:15], 0
	s_cselect_b64 s[98:99], s[46:47], s[48:49]
	v_sub_f32_e32 v103, v206, v103
	v_mul_f32_e32 v103, 0x3fb8aa3b, v103
	v_cndmask_b32_e64 v103, v232, v103, s[98:99]
	s_cmp_lg_u64 s[14:15], 0
	s_cselect_b64 s[98:99], s[54:55], s[56:57]
	s_waitcnt lgkmcnt(0)
	v_sub_f32_e32 v96, v206, v96
	v_mul_f32_e32 v96, 0x3fb8aa3b, v96
	v_cndmask_b32_e64 v96, v232, v96, s[98:99]
	s_cmp_lg_u64 s[14:15], 0
	s_cselect_b64 s[98:99], s[58:59], s[60:61]
	v_sub_f32_e32 v97, v206, v97
	v_mul_f32_e32 v97, 0x3fb8aa3b, v97
	v_cndmask_b32_e64 v97, v232, v97, s[98:99]
	s_cmp_lg_u64 s[14:15], 0
	s_cselect_b64 s[98:99], s[62:63], s[64:65]
	v_sub_f32_e32 v98, v206, v98
	v_mul_f32_e32 v98, 0x3fb8aa3b, v98
	v_sub_f32_e32 v99, v206, v99
	v_cndmask_b32_e64 v98, v232, v98, s[98:99]
	s_cmp_lg_u64 s[14:15], 0
	s_cselect_b64 s[98:99], s[66:67], s[68:69]
	v_mul_f32_e32 v99, 0x3fb8aa3b, v99
	v_exp_f32_e32 v100, v100
	v_cndmask_b32_e64 v99, v232, v99, s[98:99]
	v_exp_f32_e32 v101, v101
	v_exp_f32_e32 v102, v102
	v_exp_f32_e32 v103, v103
	v_exp_f32_e32 v96, v96
	v_exp_f32_e32 v97, v97
	v_exp_f32_e32 v98, v98
	v_exp_f32_e32 v99, v99
	v_pk_mul_f32 v[100:101], v[48:49], v[100:101]
	v_pk_mul_f32 v[102:103], v[50:51], v[102:103]
	v_pk_mul_f32 v[96:97], v[52:53], v[96:97]
	v_pk_mul_f32 v[98:99], v[54:55], v[98:99]
	v_cvt_pk_bf16_f32 v100, v100, v101
	v_cvt_pk_bf16_f32 v101, v102, v103
	v_cvt_pk_bf16_f32 v102, v96, v97
	v_cvt_pk_bf16_f32 v103, v98, v99
	ds_read2_b64 v[104:107], v110 offset0:24 offset1:26
	ds_read2_b64 v[96:99], v110 offset0:28 offset1:30
	v_add_u32_e32 v110, 0x2000, v110
	s_waitcnt lgkmcnt(1)
	v_mfma_f32_32x32x16_bf16 v[80:95], v[100:103], v[104:107], v[80:95]
	ds_read2_b64 v[104:107], v110 offset0:88 offset1:90
	s_waitcnt lgkmcnt(0)
	v_mfma_f32_32x32x16_bf16 v[64:79], v[100:103], v[104:107], v[64:79]
	ds_read_b128 v[104:107], v214 offset:448
	ds_read_b128 v[100:103], v214 offset:480
	s_cmp_lg_u64 s[14:15], 0
	s_cselect_b64 s[98:99], s[70:71], s[72:73]
	s_waitcnt lgkmcnt(1)
	v_sub_f32_e32 v104, v206, v104
	v_mul_f32_e32 v104, 0x3fb8aa3b, v104
	v_cndmask_b32_e64 v104, v232, v104, s[98:99]
	s_cmp_lg_u64 s[14:15], 0
	s_cselect_b64 s[98:99], s[78:79], s[80:81]
	v_sub_f32_e32 v105, v206, v105
	v_mul_f32_e32 v105, 0x3fb8aa3b, v105
	v_cndmask_b32_e64 v105, v232, v105, s[98:99]
	s_cmp_lg_u64 s[14:15], 0
	s_cselect_b64 s[98:99], s[82:83], s[84:85]
	v_sub_f32_e32 v106, v206, v106
	v_mul_f32_e32 v106, 0x3fb8aa3b, v106
	v_cndmask_b32_e64 v106, v232, v106, s[98:99]
	s_cmp_lg_u64 s[14:15], 0
	s_cselect_b64 s[98:99], s[86:87], s[88:89]
	v_sub_f32_e32 v107, v206, v107
	v_mul_f32_e32 v107, 0x3fb8aa3b, v107
	v_cndmask_b32_e64 v107, v232, v107, s[98:99]
	s_cmp_lg_u64 s[14:15], 0
	s_cselect_b64 s[98:99], s[90:91], s[92:93]
	s_waitcnt lgkmcnt(0)
	v_sub_f32_e32 v100, v206, v100
	v_mul_f32_e32 v100, 0x3fb8aa3b, v100
	v_sub_f32_e32 v101, v206, v101
	v_cndmask_b32_e64 v100, v232, v100, s[98:99]
	s_cmp_lg_u64 s[14:15], 0
	s_cselect_b64 s[98:99], s[94:95], s[96:97]
	v_mul_f32_e32 v101, 0x3fb8aa3b, v101
	v_exp_f32_e32 v100, v100
	v_cndmask_b32_e64 v101, v232, v101, s[98:99]
	v_exp_f32_e32 v101, v101
	v_exp_f32_e32 v104, v104
	v_exp_f32_e32 v105, v105
	v_exp_f32_e32 v106, v106
	v_pk_mul_f32 v[108:109], v[60:61], v[100:101]
	s_cmp_lg_u64 s[14:15], 0
	s_cselect_b64 s[98:99], s[2:3], s[8:9]
	v_sub_f32_e32 v100, v206, v102
	v_mul_f32_e32 v100, 0x3fb8aa3b, v100
	v_cndmask_b32_e64 v100, v232, v100, s[98:99]
	s_cmp_lg_u64 s[14:15], 0
	s_cselect_b64 s[98:99], s[0:1], s[10:11]
	v_sub_f32_e32 v101, v206, v103
	v_mul_f32_e32 v101, 0x3fb8aa3b, v101
	v_cndmask_b32_e64 v101, v232, v101, s[98:99]
	v_exp_f32_e32 v107, v107
	v_exp_f32_e32 v100, v100
	v_exp_f32_e32 v101, v101
	v_pk_mul_f32 v[104:105], v[56:57], v[104:105]
	v_pk_mul_f32 v[106:107], v[58:59], v[106:107]
	v_cvt_pk_bf16_f32 v102, v108, v109
	v_pk_mul_f32 v[112:113], v[62:63], v[100:101]
	v_cvt_pk_bf16_f32 v100, v104, v105
	v_cvt_pk_bf16_f32 v101, v106, v107
	v_cvt_pk_bf16_f32 v103, v112, v113
	s_nop 1
	v_mfma_f32_32x32x16_bf16 v[80:95], v[100:103], v[96:99], v[80:95]
	ds_read2_b64 v[96:99], v110 offset0:92 offset1:94
	s_waitcnt lgkmcnt(0)
	v_mfma_f32_32x32x16_bf16 v[64:79], v[100:103], v[96:99], v[64:79]
	s_branch .LBB0_2104
